# EpiQkv rope-table loads issued in two batches up front instead of a 16-step load-wait ladder
# speedup vs baseline: 1.0475x; 1.0016x over previous
; DI unsigned pk2(float a, float b) { f32x2 v = {a, b}; bf16x2_t r = __builtin_convertvector(v, bf16x2_t); return __builtin_bit_cast(unsigned, r); }
;     DI void operator()(gacc_t& acc, int pm, int pn, char* lds, int tid, int wr, int wc, int lane) const {
;     ...
;         if (pn < 8) {
;             const float sc = pn < 4 ? 0.18033688011112042f : 1.0f;
;             const f32x2* rbase = rope + (R0 - t0 + wr * 128 + fr) * 32 + 4 * fq;
; #pragma unroll
;             for (int m = 0; m < 8; ++m) {
;                 const float rs = rlt[m * 16] * sc;
; #pragma unroll
;                 for (int n = 0; n < 2; ++n) {
;                     const f32x4 c01 = *(const f32x4*)(rbase + m * 16 * 32 + n * 16), c23 = *(const f32x4*)(rbase + m * 16 * 32 + n * 16 + 2);
;                     const float cs_[4] = {c01.x, c01.z, c23.x, c23.z}, sn_[4] = {c01.y, c01.w, c23.y, c23.w};
;                     float o1[4], o2[4];
; #pragma unroll
;                     for (int j = 0; j < 4; ++j) {
;                         const float x1 = acc[m][n][j], x2 = acc[m][n + 2][j];
;                         o1[j] = (x1 * cs_[j] - x2 * sn_[j]) * rs; o2[j] = (x2 * cs_[j] + x1 * sn_[j]) * rs;
;                     }
;                     u32x2 w1, w2; w1.x = pk2(o1[0], o1[1]); w1.y = pk2(o1[2], o1[3]); w2.x = pk2(o2[0], o2[1]); w2.y = pk2(o2[2], o2[3]);
;                     *(u32x2*)(lbase + m * 16 * 528 + n * 32) = w1; *(u32x2*)(lbase + m * 16 * 528 + n * 32 + 64) = w2;
.LBB0_144:
	s_andn2_b64 vcc, exec, s[30:31]
	s_and_b32 s30, s19, s16
	s_cbranch_vccnz .LBB0_146
	v_add_u32_e32 v162, s16, v144
	v_subrev_u32_e32 v162, s30, v162
	v_or_b32_e32 v137, v137, v162
	v_lshlrev_b32_e32 v162, 5, v137
	v_ashrrev_i32_e32 v163, 31, v162
	v_lshl_add_u64 v[162:163], v[162:163], 3, s[8:9]
	v_ashrrev_i32_e32 v137, 31, v136
	v_lshl_add_u64 v[136:137], v[136:137], 3, v[162:163]
	ds_read_b32 v162, v146
	s_cmp_lt_i32 s17, 4
	s_cselect_b64 vcc, -1, 0
	v_mov_b32_e32 v161, 0x3e38aa3b
	v_cndmask_b32_e32 v161, 1.0, v161, vcc
	s_waitcnt lgkmcnt(0)
	v_mul_f32_e32 v166, v161, v162
	global_load_dwordx4 v[178:181], v[136:137], off
	global_load_dwordx4 v[186:189], v[136:137], off offset:16
	global_load_dwordx4 v[190:193], v[136:137], off offset:128
	global_load_dwordx4 v[194:197], v[136:137], off offset:144
	v_add_co_u32_e32 v202, vcc, 0x1000, v136
	s_nop 1
	v_addc_co_u32_e32 v203, vcc, 0, v137, vcc
	global_load_dwordx4 v[198:201], v[202:203], off
	global_load_dwordx4 v[202:205], v[202:203], off offset:16
	v_add_co_u32_e32 v210, vcc, 0x1000, v136
	s_nop 1
	v_addc_co_u32_e32 v211, vcc, 0, v137, vcc
	global_load_dwordx4 v[206:209], v[210:211], off offset:128
	global_load_dwordx4 v[210:213], v[210:211], off offset:144
	v_add_co_u32_e32 v218, vcc, 0x2000, v136
	s_nop 1
	v_addc_co_u32_e32 v219, vcc, 0, v137, vcc
	global_load_dwordx4 v[214:217], v[218:219], off
	global_load_dwordx4 v[218:221], v[218:219], off offset:16
	v_add_co_u32_e32 v226, vcc, 0x2000, v136
	s_nop 1
	v_addc_co_u32_e32 v227, vcc, 0, v137, vcc
	global_load_dwordx4 v[222:225], v[226:227], off offset:128
	global_load_dwordx4 v[226:229], v[226:227], off offset:144
	v_add_co_u32_e32 v234, vcc, 0x3000, v136
	s_nop 1
	v_addc_co_u32_e32 v235, vcc, 0, v137, vcc
	global_load_dwordx4 v[230:233], v[234:235], off
	global_load_dwordx4 v[234:237], v[234:235], off offset:16
	v_add_co_u32_e32 v242, vcc, 0x3000, v136
	s_nop 1
	v_addc_co_u32_e32 v243, vcc, 0, v137, vcc
	global_load_dwordx4 v[238:241], v[242:243], off offset:128
	global_load_dwordx4 v[242:245], v[242:243], off offset:144
	v_add_co_u32_e32 v250, vcc, 0x4000, v136
	s_nop 1
	v_addc_co_u32_e32 v251, vcc, 0, v137, vcc
	global_load_dwordx4 v[246:249], v[250:251], off
	global_load_dwordx4 v[250:253], v[250:251], off offset:16
	s_waitcnt vmcnt(16) lgkmcnt(0)
	v_mov_b32_e32 v162, v178
	v_mov_b32_e32 v163, v179
	v_mov_b32_e32 v164, v180
	v_mov_b32_e32 v165, v181
	v_mov_b32_e32 v172, v186
	v_mov_b32_e32 v173, v187
	v_mov_b32_e32 v174, v188
	v_mov_b32_e32 v175, v189
	v_mov_b32_e32 v176, v162
	v_mov_b32_e32 v177, v164
	v_mov_b32_e32 v164, v163
	v_pk_mul_f32 v[162:163], v[124:125], v[164:165]
	v_pk_mul_f32 v[124:125], v[124:125], v[176:177]
	v_pk_fma_f32 v[162:163], v[120:121], v[176:177], v[162:163] neg_lo:[0,0,1] neg_hi:[0,0,1]
	v_pk_fma_f32 v[120:121], v[120:121], v[164:165], v[124:125]
	v_mov_b32_e32 v125, v174
	v_mov_b32_e32 v174, v173
	v_mov_b32_e32 v124, v172
	v_pk_mul_f32 v[164:165], v[126:127], v[174:175]
	v_pk_mul_f32 v[162:163], v[166:167], v[162:163] op_sel_hi:[0,1]
	v_pk_fma_f32 v[164:165], v[122:123], v[124:125], v[164:165] neg_lo:[0,0,1] neg_hi:[0,0,1]
	v_pk_mul_f32 v[124:125], v[126:127], v[124:125]
	v_pk_mul_f32 v[164:165], v[166:167], v[164:165] op_sel_hi:[0,1]
	v_pk_fma_f32 v[122:123], v[122:123], v[174:175], v[124:125]
	v_pk_mul_f32 v[120:121], v[166:167], v[120:121] op_sel_hi:[0,1]
	v_pk_mul_f32 v[122:123], v[166:167], v[122:123] op_sel_hi:[0,1]
	v_cvt_pk_bf16_f32 v124, v162, v163
	v_cvt_pk_bf16_f32 v125, v164, v165
	v_cvt_pk_bf16_f32 v120, v120, v121
	v_cvt_pk_bf16_f32 v121, v122, v123
	ds_write_b64 v139, v[124:125]
	ds_write_b64 v139, v[120:121] offset:64
	s_waitcnt vmcnt(14) lgkmcnt(0)
	v_mov_b32_e32 v120, v190
	v_mov_b32_e32 v121, v191
	v_mov_b32_e32 v122, v192
	v_mov_b32_e32 v123, v193
	v_mov_b32_e32 v124, v194
	v_mov_b32_e32 v125, v195
	v_mov_b32_e32 v126, v196
	v_mov_b32_e32 v127, v197
	v_mov_b32_e32 v162, v120
	v_mov_b32_e32 v163, v122
	v_mov_b32_e32 v122, v121
	v_pk_mul_f32 v[120:121], v[116:117], v[122:123]
	v_pk_mul_f32 v[116:117], v[116:117], v[162:163]
	v_pk_fma_f32 v[120:121], v[112:113], v[162:163], v[120:121] neg_lo:[0,0,1] neg_hi:[0,0,1]
	v_pk_fma_f32 v[112:113], v[112:113], v[122:123], v[116:117]
	v_mov_b32_e32 v117, v126
	v_mov_b32_e32 v126, v125
	v_mov_b32_e32 v116, v124
	v_pk_mul_f32 v[122:123], v[118:119], v[126:127]
	v_pk_mul_f32 v[120:121], v[166:167], v[120:121] op_sel_hi:[0,1]
	v_pk_fma_f32 v[122:123], v[114:115], v[116:117], v[122:123] neg_lo:[0,0,1] neg_hi:[0,0,1]
	v_pk_mul_f32 v[116:117], v[118:119], v[116:117]
	v_pk_mul_f32 v[122:123], v[166:167], v[122:123] op_sel_hi:[0,1]
	v_pk_fma_f32 v[114:115], v[114:115], v[126:127], v[116:117]
	v_pk_mul_f32 v[112:113], v[166:167], v[112:113] op_sel_hi:[0,1]
	v_pk_mul_f32 v[114:115], v[166:167], v[114:115] op_sel_hi:[0,1]
	v_cvt_pk_bf16_f32 v116, v120, v121
	v_cvt_pk_bf16_f32 v117, v122, v123
	v_cvt_pk_bf16_f32 v112, v112, v113
	v_cvt_pk_bf16_f32 v113, v114, v115
	ds_write_b64 v139, v[116:117] offset:32
	ds_write_b64 v139, v[112:113] offset:96
	ds_read_b32 v112, v146 offset:64
	v_add_co_u32_e32 v122, vcc, s46, v136
	s_waitcnt lgkmcnt(0)
	v_mul_f32_e32 v120, v161, v112
	v_addc_co_u32_e32 v123, vcc, 0, v137, vcc
	s_waitcnt vmcnt(12) lgkmcnt(0)
; DI unsigned pk2(float a, float b) { f32x2 v = {a, b}; bf16x2_t r = __builtin_convertvector(v, bf16x2_t); return __builtin_bit_cast(unsigned, r); }
;     DI void operator()(gacc_t& acc, int pm, int pn, char* lds, int tid, int wr, int wc, int lane) const {
;     ...
;             for (int m = 0; m < 8; ++m) {
;                 const float rs = rlt[m * 16] * sc;
; #pragma unroll
;                 for (int n = 0; n < 2; ++n) {
;                     const f32x4 c01 = *(const f32x4*)(rbase + m * 16 * 32 + n * 16), c23 = *(const f32x4*)(rbase + m * 16 * 32 + n * 16 + 2);
;                     const float cs_[4] = {c01.x, c01.z, c23.x, c23.z}, sn_[4] = {c01.y, c01.w, c23.y, c23.w};
;                     float o1[4], o2[4];
; #pragma unroll
;                     for (int j = 0; j < 4; ++j) {
;                         const float x1 = acc[m][n][j], x2 = acc[m][n + 2][j];
;                         o1[j] = (x1 * cs_[j] - x2 * sn_[j]) * rs; o2[j] = (x2 * cs_[j] + x1 * sn_[j]) * rs;
;                     }
;                     u32x2 w1, w2; w1.x = pk2(o1[0], o1[1]); w1.y = pk2(o1[2], o1[3]); w2.x = pk2(o2[0], o2[1]); w2.y = pk2(o2[2], o2[3]);
;                     *(u32x2*)(lbase + m * 16 * 528 + n * 32) = w1; *(u32x2*)(lbase + m * 16 * 528 + n * 32 + 64) = w2;
	v_mov_b32_e32 v112, v198
	v_mov_b32_e32 v113, v199
	v_mov_b32_e32 v114, v200
	v_mov_b32_e32 v115, v201
	v_mov_b32_e32 v116, v202
	v_mov_b32_e32 v117, v203
	v_mov_b32_e32 v118, v204
	v_mov_b32_e32 v119, v205
	v_mov_b32_e32 v124, v112
	v_mov_b32_e32 v125, v114
	v_mov_b32_e32 v114, v113
	v_pk_mul_f32 v[112:113], v[108:109], v[114:115]
	v_pk_mul_f32 v[108:109], v[108:109], v[124:125]
	v_pk_fma_f32 v[112:113], v[104:105], v[124:125], v[112:113] neg_lo:[0,0,1] neg_hi:[0,0,1]
	v_pk_fma_f32 v[104:105], v[104:105], v[114:115], v[108:109]
	v_mov_b32_e32 v109, v118
	v_mov_b32_e32 v118, v117
	v_mov_b32_e32 v108, v116
	v_pk_mul_f32 v[114:115], v[110:111], v[118:119]
	v_pk_mul_f32 v[112:113], v[120:121], v[112:113] op_sel_hi:[0,1]
	v_pk_fma_f32 v[114:115], v[106:107], v[108:109], v[114:115] neg_lo:[0,0,1] neg_hi:[0,0,1]
	v_pk_mul_f32 v[108:109], v[110:111], v[108:109]
	v_pk_mul_f32 v[114:115], v[120:121], v[114:115] op_sel_hi:[0,1]
	v_pk_fma_f32 v[106:107], v[106:107], v[118:119], v[108:109]
	v_pk_mul_f32 v[104:105], v[120:121], v[104:105] op_sel_hi:[0,1]
	v_pk_mul_f32 v[106:107], v[120:121], v[106:107] op_sel_hi:[0,1]
	v_cvt_pk_bf16_f32 v108, v112, v113
	v_cvt_pk_bf16_f32 v109, v114, v115
	v_cvt_pk_bf16_f32 v104, v104, v105
	v_cvt_pk_bf16_f32 v105, v106, v107
	ds_write_b64 v139, v[108:109] offset:8448
	ds_write_b64 v139, v[104:105] offset:8512
	s_waitcnt vmcnt(10) lgkmcnt(0)
	v_mov_b32_e32 v104, v206
	v_mov_b32_e32 v105, v207
	v_mov_b32_e32 v106, v208
	v_mov_b32_e32 v107, v209
	v_mov_b32_e32 v108, v210
	v_mov_b32_e32 v109, v211
	v_mov_b32_e32 v110, v212
	v_mov_b32_e32 v111, v213
	v_mov_b32_e32 v112, v104
	v_mov_b32_e32 v113, v106
	v_mov_b32_e32 v106, v105
	v_pk_mul_f32 v[104:105], v[100:101], v[106:107]
	v_pk_mul_f32 v[100:101], v[100:101], v[112:113]
	v_pk_fma_f32 v[104:105], v[96:97], v[112:113], v[104:105] neg_lo:[0,0,1] neg_hi:[0,0,1]
	v_pk_fma_f32 v[96:97], v[96:97], v[106:107], v[100:101]
	v_mov_b32_e32 v101, v110
	v_mov_b32_e32 v110, v109
	v_mov_b32_e32 v100, v108
	v_pk_mul_f32 v[106:107], v[102:103], v[110:111]
	v_pk_mul_f32 v[104:105], v[120:121], v[104:105] op_sel_hi:[0,1]
	v_pk_fma_f32 v[106:107], v[98:99], v[100:101], v[106:107] neg_lo:[0,0,1] neg_hi:[0,0,1]
	v_pk_mul_f32 v[100:101], v[102:103], v[100:101]
	v_pk_mul_f32 v[106:107], v[120:121], v[106:107] op_sel_hi:[0,1]
	v_pk_fma_f32 v[98:99], v[98:99], v[110:111], v[100:101]
	v_pk_mul_f32 v[96:97], v[120:121], v[96:97] op_sel_hi:[0,1]
	v_pk_mul_f32 v[98:99], v[120:121], v[98:99] op_sel_hi:[0,1]
	v_cvt_pk_bf16_f32 v100, v104, v105
	v_cvt_pk_bf16_f32 v101, v106, v107
	v_cvt_pk_bf16_f32 v96, v96, v97
	v_cvt_pk_bf16_f32 v97, v98, v99
	ds_write_b64 v139, v[100:101] offset:8480
	ds_write_b64 v139, v[96:97] offset:8544
	ds_read_b32 v96, v146 offset:128
	v_add_co_u32_e32 v106, vcc, s86, v136
	s_waitcnt lgkmcnt(0)
	v_mul_f32_e32 v104, v161, v96
	v_addc_co_u32_e32 v107, vcc, 0, v137, vcc
	s_waitcnt vmcnt(8) lgkmcnt(0)
	v_mov_b32_e32 v96, v214
	v_mov_b32_e32 v97, v215
	v_mov_b32_e32 v98, v216
	v_mov_b32_e32 v99, v217
	v_mov_b32_e32 v100, v218
	v_mov_b32_e32 v101, v219
	v_mov_b32_e32 v102, v220
	v_mov_b32_e32 v103, v221
	v_mov_b32_e32 v108, v96
	v_mov_b32_e32 v109, v98
	v_mov_b32_e32 v98, v97
	v_pk_mul_f32 v[96:97], v[92:93], v[98:99]
	v_pk_mul_f32 v[92:93], v[92:93], v[108:109]
	v_pk_fma_f32 v[96:97], v[88:89], v[108:109], v[96:97] neg_lo:[0,0,1] neg_hi:[0,0,1]
	v_pk_fma_f32 v[88:89], v[88:89], v[98:99], v[92:93]
	v_mov_b32_e32 v93, v102
	v_mov_b32_e32 v102, v101
	v_mov_b32_e32 v92, v100
	v_pk_mul_f32 v[98:99], v[94:95], v[102:103]
	v_pk_mul_f32 v[96:97], v[104:105], v[96:97] op_sel_hi:[0,1]
	v_pk_fma_f32 v[98:99], v[90:91], v[92:93], v[98:99] neg_lo:[0,0,1] neg_hi:[0,0,1]
	v_pk_mul_f32 v[92:93], v[94:95], v[92:93]
	v_pk_mul_f32 v[98:99], v[104:105], v[98:99] op_sel_hi:[0,1]
	v_pk_fma_f32 v[90:91], v[90:91], v[102:103], v[92:93]
	v_pk_mul_f32 v[88:89], v[104:105], v[88:89] op_sel_hi:[0,1]
	v_pk_mul_f32 v[90:91], v[104:105], v[90:91] op_sel_hi:[0,1]
	v_cvt_pk_bf16_f32 v92, v96, v97
	v_cvt_pk_bf16_f32 v93, v98, v99
	v_cvt_pk_bf16_f32 v88, v88, v89
	v_cvt_pk_bf16_f32 v89, v90, v91
	ds_write_b64 v139, v[92:93] offset:16896
	ds_write_b64 v139, v[88:89] offset:16960
	s_waitcnt vmcnt(6) lgkmcnt(0)
	v_mov_b32_e32 v88, v222
	v_mov_b32_e32 v89, v223
	v_mov_b32_e32 v90, v224
	v_mov_b32_e32 v91, v225
	v_mov_b32_e32 v92, v226
	v_mov_b32_e32 v93, v227
	v_mov_b32_e32 v94, v228
	v_mov_b32_e32 v95, v229
	v_mov_b32_e32 v96, v88
	v_mov_b32_e32 v97, v90
	v_mov_b32_e32 v90, v89
	v_pk_mul_f32 v[88:89], v[84:85], v[90:91]
	v_pk_mul_f32 v[84:85], v[84:85], v[96:97]
	v_pk_fma_f32 v[88:89], v[80:81], v[96:97], v[88:89] neg_lo:[0,0,1] neg_hi:[0,0,1]
	v_pk_fma_f32 v[80:81], v[80:81], v[90:91], v[84:85]
	v_mov_b32_e32 v85, v94
	v_mov_b32_e32 v94, v93
	v_mov_b32_e32 v84, v92
	v_pk_mul_f32 v[90:91], v[86:87], v[94:95]
	v_pk_mul_f32 v[88:89], v[104:105], v[88:89] op_sel_hi:[0,1]
	v_pk_fma_f32 v[90:91], v[82:83], v[84:85], v[90:91] neg_lo:[0,0,1] neg_hi:[0,0,1]
	v_pk_mul_f32 v[84:85], v[86:87], v[84:85]
	v_pk_mul_f32 v[90:91], v[104:105], v[90:91] op_sel_hi:[0,1]
	v_pk_fma_f32 v[82:83], v[82:83], v[94:95], v[84:85]
	v_pk_mul_f32 v[80:81], v[104:105], v[80:81] op_sel_hi:[0,1]
	v_pk_mul_f32 v[82:83], v[104:105], v[82:83] op_sel_hi:[0,1]
	v_cvt_pk_bf16_f32 v84, v88, v89
	v_cvt_pk_bf16_f32 v85, v90, v91
	v_cvt_pk_bf16_f32 v80, v80, v81
	v_cvt_pk_bf16_f32 v81, v82, v83
	ds_write_b64 v139, v[84:85] offset:16928
	ds_write_b64 v139, v[80:81] offset:16992
	ds_read_b32 v80, v146 offset:192
	s_movk_i32 s19, 0x3000
	v_add_co_u32_e32 v90, vcc, s19, v136
	s_waitcnt lgkmcnt(0)
	v_mul_f32_e32 v88, v161, v80
	v_addc_co_u32_e32 v91, vcc, 0, v137, vcc
	s_waitcnt vmcnt(4) lgkmcnt(0)
; DI unsigned pk2(float a, float b) { f32x2 v = {a, b}; bf16x2_t r = __builtin_convertvector(v, bf16x2_t); return __builtin_bit_cast(unsigned, r); }
;     DI void operator()(gacc_t& acc, int pm, int pn, char* lds, int tid, int wr, int wc, int lane) const {
;     ...
;             for (int m = 0; m < 8; ++m) {
;                 const float rs = rlt[m * 16] * sc;
; #pragma unroll
;                 for (int n = 0; n < 2; ++n) {
;                     const f32x4 c01 = *(const f32x4*)(rbase + m * 16 * 32 + n * 16), c23 = *(const f32x4*)(rbase + m * 16 * 32 + n * 16 + 2);
;                     const float cs_[4] = {c01.x, c01.z, c23.x, c23.z}, sn_[4] = {c01.y, c01.w, c23.y, c23.w};
;                     float o1[4], o2[4];
; #pragma unroll
;                     for (int j = 0; j < 4; ++j) {
;                         const float x1 = acc[m][n][j], x2 = acc[m][n + 2][j];
;                         o1[j] = (x1 * cs_[j] - x2 * sn_[j]) * rs; o2[j] = (x2 * cs_[j] + x1 * sn_[j]) * rs;
;                     }
;                     u32x2 w1, w2; w1.x = pk2(o1[0], o1[1]); w1.y = pk2(o1[2], o1[3]); w2.x = pk2(o2[0], o2[1]); w2.y = pk2(o2[2], o2[3]);
;                     *(u32x2*)(lbase + m * 16 * 528 + n * 32) = w1; *(u32x2*)(lbase + m * 16 * 528 + n * 32 + 64) = w2;
	v_mov_b32_e32 v80, v230
	v_mov_b32_e32 v81, v231
	v_mov_b32_e32 v82, v232
	v_mov_b32_e32 v83, v233
	v_mov_b32_e32 v84, v234
	v_mov_b32_e32 v85, v235
	v_mov_b32_e32 v86, v236
	v_mov_b32_e32 v87, v237
	v_add_co_u32_e32 v186, vcc, 0x4000, v136
	s_nop 1
	v_addc_co_u32_e32 v187, vcc, 0, v137, vcc
	global_load_dwordx4 v[178:181], v[186:187], off offset:128
	global_load_dwordx4 v[186:189], v[186:187], off offset:144
	v_add_co_u32_e32 v194, vcc, 0x5000, v136
	s_nop 1
	v_addc_co_u32_e32 v195, vcc, 0, v137, vcc
	global_load_dwordx4 v[190:193], v[194:195], off
	global_load_dwordx4 v[194:197], v[194:195], off offset:16
	v_add_co_u32_e32 v202, vcc, 0x5000, v136
	s_nop 1
	v_addc_co_u32_e32 v203, vcc, 0, v137, vcc
	global_load_dwordx4 v[198:201], v[202:203], off offset:128
	global_load_dwordx4 v[202:205], v[202:203], off offset:144
	v_add_co_u32_e32 v210, vcc, 0x6000, v136
	s_nop 1
	v_addc_co_u32_e32 v211, vcc, 0, v137, vcc
	global_load_dwordx4 v[206:209], v[210:211], off
	global_load_dwordx4 v[210:213], v[210:211], off offset:16
	v_add_co_u32_e32 v218, vcc, 0x6000, v136
	s_nop 1
	v_addc_co_u32_e32 v219, vcc, 0, v137, vcc
	global_load_dwordx4 v[214:217], v[218:219], off offset:128
	global_load_dwordx4 v[218:221], v[218:219], off offset:144
	v_add_co_u32_e32 v226, vcc, 0x7000, v136
	s_nop 1
	v_addc_co_u32_e32 v227, vcc, 0, v137, vcc
	global_load_dwordx4 v[222:225], v[226:227], off
	global_load_dwordx4 v[226:229], v[226:227], off offset:16
	v_add_co_u32_e32 v234, vcc, 0x7000, v136
	s_nop 1
	v_addc_co_u32_e32 v235, vcc, 0, v137, vcc
	global_load_dwordx4 v[230:233], v[234:235], off offset:128
	global_load_dwordx4 v[234:237], v[234:235], off offset:144
	v_mov_b32_e32 v92, v80
	v_mov_b32_e32 v93, v82
	v_mov_b32_e32 v82, v81
	v_pk_mul_f32 v[80:81], v[76:77], v[82:83]
	v_pk_mul_f32 v[76:77], v[76:77], v[92:93]
	v_pk_fma_f32 v[80:81], v[72:73], v[92:93], v[80:81] neg_lo:[0,0,1] neg_hi:[0,0,1]
	v_pk_fma_f32 v[72:73], v[72:73], v[82:83], v[76:77]
	v_mov_b32_e32 v77, v86
	v_mov_b32_e32 v86, v85
	v_mov_b32_e32 v76, v84
	v_pk_mul_f32 v[82:83], v[78:79], v[86:87]
	v_pk_mul_f32 v[80:81], v[88:89], v[80:81] op_sel_hi:[0,1]
	v_pk_fma_f32 v[82:83], v[74:75], v[76:77], v[82:83] neg_lo:[0,0,1] neg_hi:[0,0,1]
	v_pk_mul_f32 v[76:77], v[78:79], v[76:77]
	v_pk_mul_f32 v[82:83], v[88:89], v[82:83] op_sel_hi:[0,1]
	v_pk_fma_f32 v[74:75], v[74:75], v[86:87], v[76:77]
	v_pk_mul_f32 v[72:73], v[88:89], v[72:73] op_sel_hi:[0,1]
	v_pk_mul_f32 v[74:75], v[88:89], v[74:75] op_sel_hi:[0,1]
	v_cvt_pk_bf16_f32 v76, v80, v81
	v_cvt_pk_bf16_f32 v77, v82, v83
	v_cvt_pk_bf16_f32 v72, v72, v73
	v_cvt_pk_bf16_f32 v73, v74, v75
	ds_write_b64 v139, v[76:77] offset:25344
	ds_write_b64 v139, v[72:73] offset:25408
	s_waitcnt vmcnt(16) lgkmcnt(0)
	v_mov_b32_e32 v72, v238
	v_mov_b32_e32 v73, v239
	v_mov_b32_e32 v74, v240
	v_mov_b32_e32 v75, v241
	v_mov_b32_e32 v76, v242
	v_mov_b32_e32 v77, v243
	v_mov_b32_e32 v78, v244
	v_mov_b32_e32 v79, v245
	v_mov_b32_e32 v80, v72
	v_mov_b32_e32 v81, v74
	v_mov_b32_e32 v74, v73
	v_pk_mul_f32 v[72:73], v[68:69], v[74:75]
	v_pk_mul_f32 v[68:69], v[68:69], v[80:81]
	v_pk_fma_f32 v[72:73], v[64:65], v[80:81], v[72:73] neg_lo:[0,0,1] neg_hi:[0,0,1]
	v_pk_fma_f32 v[64:65], v[64:65], v[74:75], v[68:69]
	v_mov_b32_e32 v69, v78
	v_mov_b32_e32 v78, v77
	v_mov_b32_e32 v68, v76
	v_pk_mul_f32 v[74:75], v[70:71], v[78:79]
	v_pk_mul_f32 v[72:73], v[88:89], v[72:73] op_sel_hi:[0,1]
	v_pk_fma_f32 v[74:75], v[66:67], v[68:69], v[74:75] neg_lo:[0,0,1] neg_hi:[0,0,1]
	v_pk_mul_f32 v[68:69], v[70:71], v[68:69]
	v_pk_mul_f32 v[74:75], v[88:89], v[74:75] op_sel_hi:[0,1]
	v_pk_fma_f32 v[66:67], v[66:67], v[78:79], v[68:69]
	v_pk_mul_f32 v[64:65], v[88:89], v[64:65] op_sel_hi:[0,1]
	v_pk_mul_f32 v[66:67], v[88:89], v[66:67] op_sel_hi:[0,1]
	v_cvt_pk_bf16_f32 v68, v72, v73
	v_cvt_pk_bf16_f32 v69, v74, v75
	v_cvt_pk_bf16_f32 v64, v64, v65
	v_cvt_pk_bf16_f32 v65, v66, v67
	ds_write_b64 v139, v[68:69] offset:25376
	ds_write_b64 v139, v[64:65] offset:25440
	ds_read_b32 v64, v146 offset:256
	s_movk_i32 s19, 0x4000
	v_add_co_u32_e32 v74, vcc, s19, v136
	s_waitcnt lgkmcnt(0)
	v_mul_f32_e32 v72, v161, v64
	v_addc_co_u32_e32 v75, vcc, 0, v137, vcc
	s_waitcnt vmcnt(14) lgkmcnt(0)
	v_mov_b32_e32 v64, v246
	v_mov_b32_e32 v65, v247
	v_mov_b32_e32 v66, v248
	v_mov_b32_e32 v67, v249
	v_mov_b32_e32 v68, v250
	v_mov_b32_e32 v69, v251
	v_mov_b32_e32 v70, v252
	v_mov_b32_e32 v71, v253
	v_mov_b32_e32 v76, v64
	v_mov_b32_e32 v77, v66
	v_mov_b32_e32 v66, v65
	v_pk_mul_f32 v[64:65], v[60:61], v[66:67]
	v_pk_mul_f32 v[60:61], v[60:61], v[76:77]
	v_pk_fma_f32 v[64:65], v[56:57], v[76:77], v[64:65] neg_lo:[0,0,1] neg_hi:[0,0,1]
	v_pk_fma_f32 v[56:57], v[56:57], v[66:67], v[60:61]
	v_mov_b32_e32 v61, v70
	v_mov_b32_e32 v70, v69
	v_mov_b32_e32 v60, v68
	v_pk_mul_f32 v[66:67], v[62:63], v[70:71]
	v_pk_mul_f32 v[64:65], v[72:73], v[64:65] op_sel_hi:[0,1]
	v_pk_fma_f32 v[66:67], v[58:59], v[60:61], v[66:67] neg_lo:[0,0,1] neg_hi:[0,0,1]
	v_pk_mul_f32 v[60:61], v[62:63], v[60:61]
	v_pk_mul_f32 v[66:67], v[72:73], v[66:67] op_sel_hi:[0,1]
	v_pk_fma_f32 v[58:59], v[58:59], v[70:71], v[60:61]
	v_pk_mul_f32 v[56:57], v[72:73], v[56:57] op_sel_hi:[0,1]
	v_pk_mul_f32 v[58:59], v[72:73], v[58:59] op_sel_hi:[0,1]
	v_cvt_pk_bf16_f32 v60, v64, v65
	v_cvt_pk_bf16_f32 v61, v66, v67
	v_cvt_pk_bf16_f32 v56, v56, v57
	v_cvt_pk_bf16_f32 v57, v58, v59
	ds_write_b64 v139, v[60:61] offset:33792
	ds_write_b64 v139, v[56:57] offset:33856
	s_waitcnt vmcnt(12) lgkmcnt(0)
; DI unsigned pk2(float a, float b) { f32x2 v = {a, b}; bf16x2_t r = __builtin_convertvector(v, bf16x2_t); return __builtin_bit_cast(unsigned, r); }
;     DI void operator()(gacc_t& acc, int pm, int pn, char* lds, int tid, int wr, int wc, int lane) const {
;     ...
;             for (int m = 0; m < 8; ++m) {
;                 const float rs = rlt[m * 16] * sc;
; #pragma unroll
;                 for (int n = 0; n < 2; ++n) {
;                     const f32x4 c01 = *(const f32x4*)(rbase + m * 16 * 32 + n * 16), c23 = *(const f32x4*)(rbase + m * 16 * 32 + n * 16 + 2);
;                     const float cs_[4] = {c01.x, c01.z, c23.x, c23.z}, sn_[4] = {c01.y, c01.w, c23.y, c23.w};
;                     float o1[4], o2[4];
; #pragma unroll
;                     for (int j = 0; j < 4; ++j) {
;                         const float x1 = acc[m][n][j], x2 = acc[m][n + 2][j];
;                         o1[j] = (x1 * cs_[j] - x2 * sn_[j]) * rs; o2[j] = (x2 * cs_[j] + x1 * sn_[j]) * rs;
;                     }
;                     u32x2 w1, w2; w1.x = pk2(o1[0], o1[1]); w1.y = pk2(o1[2], o1[3]); w2.x = pk2(o2[0], o2[1]); w2.y = pk2(o2[2], o2[3]);
;                     *(u32x2*)(lbase + m * 16 * 528 + n * 32) = w1; *(u32x2*)(lbase + m * 16 * 528 + n * 32 + 64) = w2;
	v_mov_b32_e32 v56, v178
	v_mov_b32_e32 v57, v179
	v_mov_b32_e32 v58, v180
	v_mov_b32_e32 v59, v181
	v_mov_b32_e32 v60, v186
	v_mov_b32_e32 v61, v187
	v_mov_b32_e32 v62, v188
	v_mov_b32_e32 v63, v189
	v_mov_b32_e32 v64, v56
	v_mov_b32_e32 v65, v58
	v_mov_b32_e32 v58, v57
	v_pk_mul_f32 v[56:57], v[52:53], v[58:59]
	v_pk_mul_f32 v[52:53], v[52:53], v[64:65]
	v_pk_fma_f32 v[56:57], v[48:49], v[64:65], v[56:57] neg_lo:[0,0,1] neg_hi:[0,0,1]
	v_pk_fma_f32 v[48:49], v[48:49], v[58:59], v[52:53]
	v_mov_b32_e32 v53, v62
	v_mov_b32_e32 v62, v61
	v_mov_b32_e32 v52, v60
	v_pk_mul_f32 v[58:59], v[54:55], v[62:63]
	v_pk_mul_f32 v[56:57], v[72:73], v[56:57] op_sel_hi:[0,1]
	v_pk_fma_f32 v[58:59], v[50:51], v[52:53], v[58:59] neg_lo:[0,0,1] neg_hi:[0,0,1]
	v_pk_mul_f32 v[52:53], v[54:55], v[52:53]
	v_pk_mul_f32 v[58:59], v[72:73], v[58:59] op_sel_hi:[0,1]
	v_pk_fma_f32 v[50:51], v[50:51], v[62:63], v[52:53]
	v_pk_mul_f32 v[48:49], v[72:73], v[48:49] op_sel_hi:[0,1]
	v_pk_mul_f32 v[50:51], v[72:73], v[50:51] op_sel_hi:[0,1]
	v_cvt_pk_bf16_f32 v52, v56, v57
	v_cvt_pk_bf16_f32 v53, v58, v59
	v_cvt_pk_bf16_f32 v48, v48, v49
	v_cvt_pk_bf16_f32 v49, v50, v51
	ds_write_b64 v139, v[52:53] offset:33824
	ds_write_b64 v139, v[48:49] offset:33888
	ds_read_b32 v48, v146 offset:320
	s_movk_i32 s19, 0x5000
	v_add_co_u32_e32 v58, vcc, s19, v136
	s_waitcnt lgkmcnt(0)
	v_mul_f32_e32 v56, v161, v48
	v_addc_co_u32_e32 v59, vcc, 0, v137, vcc
	s_waitcnt vmcnt(10) lgkmcnt(0)
	v_mov_b32_e32 v48, v190
	v_mov_b32_e32 v49, v191
	v_mov_b32_e32 v50, v192
	v_mov_b32_e32 v51, v193
	v_mov_b32_e32 v52, v194
	v_mov_b32_e32 v53, v195
	v_mov_b32_e32 v54, v196
	v_mov_b32_e32 v55, v197
	v_mov_b32_e32 v60, v48
	v_mov_b32_e32 v61, v50
	v_mov_b32_e32 v50, v49
	v_pk_mul_f32 v[48:49], v[44:45], v[50:51]
	v_pk_mul_f32 v[44:45], v[44:45], v[60:61]
	v_pk_fma_f32 v[48:49], v[40:41], v[60:61], v[48:49] neg_lo:[0,0,1] neg_hi:[0,0,1]
	v_pk_fma_f32 v[40:41], v[40:41], v[50:51], v[44:45]
	v_mov_b32_e32 v45, v54
	v_mov_b32_e32 v54, v53
	v_mov_b32_e32 v44, v52
	v_pk_mul_f32 v[50:51], v[46:47], v[54:55]
	v_pk_mul_f32 v[48:49], v[56:57], v[48:49] op_sel_hi:[0,1]
	v_pk_fma_f32 v[50:51], v[42:43], v[44:45], v[50:51] neg_lo:[0,0,1] neg_hi:[0,0,1]
	v_pk_mul_f32 v[44:45], v[46:47], v[44:45]
	v_pk_mul_f32 v[50:51], v[56:57], v[50:51] op_sel_hi:[0,1]
	v_pk_fma_f32 v[42:43], v[42:43], v[54:55], v[44:45]
	v_pk_mul_f32 v[40:41], v[56:57], v[40:41] op_sel_hi:[0,1]
	v_pk_mul_f32 v[42:43], v[56:57], v[42:43] op_sel_hi:[0,1]
	v_cvt_pk_bf16_f32 v44, v48, v49
	v_cvt_pk_bf16_f32 v45, v50, v51
	v_cvt_pk_bf16_f32 v40, v40, v41
	v_cvt_pk_bf16_f32 v41, v42, v43
	ds_write_b64 v139, v[44:45] offset:42240
	ds_write_b64 v139, v[40:41] offset:42304
	s_waitcnt vmcnt(8) lgkmcnt(0)
	v_mov_b32_e32 v40, v198
	v_mov_b32_e32 v41, v199
	v_mov_b32_e32 v42, v200
	v_mov_b32_e32 v43, v201
	v_mov_b32_e32 v44, v202
	v_mov_b32_e32 v45, v203
	v_mov_b32_e32 v46, v204
	v_mov_b32_e32 v47, v205
	v_mov_b32_e32 v48, v40
	v_mov_b32_e32 v49, v42
	v_mov_b32_e32 v42, v41
	v_pk_mul_f32 v[40:41], v[36:37], v[42:43]
	v_pk_mul_f32 v[36:37], v[36:37], v[48:49]
	v_pk_fma_f32 v[40:41], v[32:33], v[48:49], v[40:41] neg_lo:[0,0,1] neg_hi:[0,0,1]
	v_pk_fma_f32 v[32:33], v[32:33], v[42:43], v[36:37]
	v_mov_b32_e32 v37, v46
	v_mov_b32_e32 v46, v45
	v_mov_b32_e32 v36, v44
	v_pk_mul_f32 v[42:43], v[38:39], v[46:47]
	v_pk_mul_f32 v[40:41], v[56:57], v[40:41] op_sel_hi:[0,1]
	v_pk_fma_f32 v[42:43], v[34:35], v[36:37], v[42:43] neg_lo:[0,0,1] neg_hi:[0,0,1]
	v_pk_mul_f32 v[36:37], v[38:39], v[36:37]
	v_pk_mul_f32 v[42:43], v[56:57], v[42:43] op_sel_hi:[0,1]
	v_pk_fma_f32 v[34:35], v[34:35], v[46:47], v[36:37]
	v_pk_mul_f32 v[32:33], v[56:57], v[32:33] op_sel_hi:[0,1]
	v_pk_mul_f32 v[34:35], v[56:57], v[34:35] op_sel_hi:[0,1]
	v_cvt_pk_bf16_f32 v36, v40, v41
	v_cvt_pk_bf16_f32 v37, v42, v43
	v_cvt_pk_bf16_f32 v32, v32, v33
	v_cvt_pk_bf16_f32 v33, v34, v35
	ds_write_b64 v139, v[36:37] offset:42272
	ds_write_b64 v139, v[32:33] offset:42336
	ds_read_b32 v32, v146 offset:384
	s_movk_i32 s19, 0x6000
	v_add_co_u32_e32 v42, vcc, s19, v136
	s_waitcnt lgkmcnt(0)
	v_mul_f32_e32 v40, v161, v32
	v_addc_co_u32_e32 v43, vcc, 0, v137, vcc
	s_waitcnt vmcnt(6) lgkmcnt(0)
; DI unsigned pk2(float a, float b) { f32x2 v = {a, b}; bf16x2_t r = __builtin_convertvector(v, bf16x2_t); return __builtin_bit_cast(unsigned, r); }
;     DI void operator()(gacc_t& acc, int pm, int pn, char* lds, int tid, int wr, int wc, int lane) const {
;     ...
;             for (int m = 0; m < 8; ++m) {
;                 const float rs = rlt[m * 16] * sc;
; #pragma unroll
;                 for (int n = 0; n < 2; ++n) {
;                     const f32x4 c01 = *(const f32x4*)(rbase + m * 16 * 32 + n * 16), c23 = *(const f32x4*)(rbase + m * 16 * 32 + n * 16 + 2);
;                     const float cs_[4] = {c01.x, c01.z, c23.x, c23.z}, sn_[4] = {c01.y, c01.w, c23.y, c23.w};
;                     float o1[4], o2[4];
; #pragma unroll
;                     for (int j = 0; j < 4; ++j) {
;                         const float x1 = acc[m][n][j], x2 = acc[m][n + 2][j];
;                         o1[j] = (x1 * cs_[j] - x2 * sn_[j]) * rs; o2[j] = (x2 * cs_[j] + x1 * sn_[j]) * rs;
;                     }
;                     u32x2 w1, w2; w1.x = pk2(o1[0], o1[1]); w1.y = pk2(o1[2], o1[3]); w2.x = pk2(o2[0], o2[1]); w2.y = pk2(o2[2], o2[3]);
;                     *(u32x2*)(lbase + m * 16 * 528 + n * 32) = w1; *(u32x2*)(lbase + m * 16 * 528 + n * 32 + 64) = w2;
	v_mov_b32_e32 v32, v206
	v_mov_b32_e32 v33, v207
	v_mov_b32_e32 v34, v208
	v_mov_b32_e32 v35, v209
	v_mov_b32_e32 v36, v210
	v_mov_b32_e32 v37, v211
	v_mov_b32_e32 v38, v212
	v_mov_b32_e32 v39, v213
	v_mov_b32_e32 v44, v32
	v_mov_b32_e32 v45, v34
	v_mov_b32_e32 v34, v33
	v_pk_mul_f32 v[32:33], v[28:29], v[34:35]
	v_pk_mul_f32 v[28:29], v[28:29], v[44:45]
	v_pk_fma_f32 v[32:33], v[24:25], v[44:45], v[32:33] neg_lo:[0,0,1] neg_hi:[0,0,1]
	v_pk_fma_f32 v[24:25], v[24:25], v[34:35], v[28:29]
	v_mov_b32_e32 v29, v38
	v_mov_b32_e32 v38, v37
	v_mov_b32_e32 v28, v36
	v_pk_mul_f32 v[34:35], v[30:31], v[38:39]
	v_pk_mul_f32 v[32:33], v[40:41], v[32:33] op_sel_hi:[0,1]
	v_pk_fma_f32 v[34:35], v[26:27], v[28:29], v[34:35] neg_lo:[0,0,1] neg_hi:[0,0,1]
	v_pk_mul_f32 v[28:29], v[30:31], v[28:29]
	v_pk_mul_f32 v[34:35], v[40:41], v[34:35] op_sel_hi:[0,1]
	v_pk_fma_f32 v[26:27], v[26:27], v[38:39], v[28:29]
	v_pk_mul_f32 v[24:25], v[40:41], v[24:25] op_sel_hi:[0,1]
	v_pk_mul_f32 v[26:27], v[40:41], v[26:27] op_sel_hi:[0,1]
	v_cvt_pk_bf16_f32 v28, v32, v33
	v_cvt_pk_bf16_f32 v29, v34, v35
	v_cvt_pk_bf16_f32 v24, v24, v25
	v_cvt_pk_bf16_f32 v25, v26, v27
	ds_write_b64 v139, v[28:29] offset:50688
	ds_write_b64 v139, v[24:25] offset:50752
	s_waitcnt vmcnt(4) lgkmcnt(0)
	v_mov_b32_e32 v24, v214
	v_mov_b32_e32 v25, v215
	v_mov_b32_e32 v26, v216
	v_mov_b32_e32 v27, v217
	v_mov_b32_e32 v28, v218
	v_mov_b32_e32 v29, v219
	v_mov_b32_e32 v30, v220
	v_mov_b32_e32 v31, v221
	v_mov_b32_e32 v32, v24
	v_mov_b32_e32 v33, v26
	v_mov_b32_e32 v26, v25
	v_pk_mul_f32 v[24:25], v[20:21], v[26:27]
	v_pk_mul_f32 v[20:21], v[20:21], v[32:33]
	v_pk_fma_f32 v[24:25], v[16:17], v[32:33], v[24:25] neg_lo:[0,0,1] neg_hi:[0,0,1]
	v_pk_fma_f32 v[16:17], v[16:17], v[26:27], v[20:21]
	v_mov_b32_e32 v21, v30
	v_mov_b32_e32 v30, v29
	v_mov_b32_e32 v20, v28
	v_pk_mul_f32 v[26:27], v[22:23], v[30:31]
	v_pk_mul_f32 v[24:25], v[40:41], v[24:25] op_sel_hi:[0,1]
	v_pk_fma_f32 v[26:27], v[18:19], v[20:21], v[26:27] neg_lo:[0,0,1] neg_hi:[0,0,1]
	v_pk_mul_f32 v[20:21], v[22:23], v[20:21]
	v_pk_mul_f32 v[26:27], v[40:41], v[26:27] op_sel_hi:[0,1]
	v_pk_fma_f32 v[18:19], v[18:19], v[30:31], v[20:21]
	v_pk_mul_f32 v[16:17], v[40:41], v[16:17] op_sel_hi:[0,1]
	v_pk_mul_f32 v[18:19], v[40:41], v[18:19] op_sel_hi:[0,1]
	v_cvt_pk_bf16_f32 v20, v24, v25
	v_cvt_pk_bf16_f32 v21, v26, v27
	v_cvt_pk_bf16_f32 v16, v16, v17
	v_cvt_pk_bf16_f32 v17, v18, v19
	ds_write_b64 v139, v[20:21] offset:50720
	ds_write_b64 v139, v[16:17] offset:50784
	ds_read_b32 v16, v146 offset:448
	s_movk_i32 s19, 0x7000
	v_add_co_u32_e32 v26, vcc, s19, v136
	s_waitcnt lgkmcnt(0)
	v_mul_f32_e32 v24, v161, v16
	v_addc_co_u32_e32 v27, vcc, 0, v137, vcc
	s_waitcnt vmcnt(2) lgkmcnt(0)
	v_mov_b32_e32 v16, v222
	v_mov_b32_e32 v17, v223
	v_mov_b32_e32 v18, v224
	v_mov_b32_e32 v19, v225
	v_mov_b32_e32 v20, v226
	v_mov_b32_e32 v21, v227
	v_mov_b32_e32 v22, v228
	v_mov_b32_e32 v23, v229
	v_mov_b32_e32 v28, v16
	v_mov_b32_e32 v29, v18
	v_mov_b32_e32 v18, v17
	v_pk_mul_f32 v[16:17], v[12:13], v[18:19]
	v_pk_mul_f32 v[12:13], v[12:13], v[28:29]
	v_pk_fma_f32 v[16:17], v[8:9], v[28:29], v[16:17] neg_lo:[0,0,1] neg_hi:[0,0,1]
	v_pk_fma_f32 v[8:9], v[8:9], v[18:19], v[12:13]
	v_mov_b32_e32 v13, v22
	v_mov_b32_e32 v22, v21
	v_mov_b32_e32 v12, v20
	v_pk_mul_f32 v[18:19], v[14:15], v[22:23]
	v_pk_mul_f32 v[16:17], v[24:25], v[16:17] op_sel_hi:[0,1]
	v_pk_fma_f32 v[18:19], v[10:11], v[12:13], v[18:19] neg_lo:[0,0,1] neg_hi:[0,0,1]
	v_pk_mul_f32 v[12:13], v[14:15], v[12:13]
	v_pk_mul_f32 v[18:19], v[24:25], v[18:19] op_sel_hi:[0,1]
	v_pk_fma_f32 v[10:11], v[10:11], v[22:23], v[12:13]
	v_pk_mul_f32 v[8:9], v[24:25], v[8:9] op_sel_hi:[0,1]
	v_pk_mul_f32 v[10:11], v[24:25], v[10:11] op_sel_hi:[0,1]
	v_cvt_pk_bf16_f32 v12, v16, v17
	v_cvt_pk_bf16_f32 v13, v18, v19
	v_cvt_pk_bf16_f32 v8, v8, v9
	v_cvt_pk_bf16_f32 v9, v10, v11
	ds_write_b64 v139, v[12:13] offset:59136
	ds_write_b64 v139, v[8:9] offset:59200
	s_waitcnt vmcnt(0) lgkmcnt(0)
	v_mov_b32_e32 v8, v230
	v_mov_b32_e32 v9, v231
	v_mov_b32_e32 v10, v232
	v_mov_b32_e32 v11, v233
	v_mov_b32_e32 v12, v234
	v_mov_b32_e32 v13, v235
	v_mov_b32_e32 v14, v236
	v_mov_b32_e32 v15, v237
	v_mov_b32_e32 v16, v8
	v_mov_b32_e32 v17, v10
	v_mov_b32_e32 v10, v9
	v_pk_mul_f32 v[8:9], v[4:5], v[10:11]
	v_pk_mul_f32 v[4:5], v[4:5], v[16:17]
	v_pk_fma_f32 v[8:9], v[0:1], v[16:17], v[8:9] neg_lo:[0,0,1] neg_hi:[0,0,1]
	v_pk_fma_f32 v[0:1], v[0:1], v[10:11], v[4:5]
	v_mov_b32_e32 v5, v14
	v_mov_b32_e32 v14, v13
	v_mov_b32_e32 v4, v12
	v_pk_mul_f32 v[10:11], v[6:7], v[14:15]
	v_pk_mul_f32 v[8:9], v[24:25], v[8:9] op_sel_hi:[0,1]
	v_pk_fma_f32 v[10:11], v[2:3], v[4:5], v[10:11] neg_lo:[0,0,1] neg_hi:[0,0,1]
	v_pk_mul_f32 v[4:5], v[6:7], v[4:5]
	v_pk_mul_f32 v[10:11], v[24:25], v[10:11] op_sel_hi:[0,1]
	v_pk_fma_f32 v[2:3], v[2:3], v[14:15], v[4:5]
	v_pk_mul_f32 v[0:1], v[24:25], v[0:1] op_sel_hi:[0,1]
	v_pk_mul_f32 v[2:3], v[24:25], v[2:3] op_sel_hi:[0,1]
	v_cvt_pk_bf16_f32 v4, v8, v9
	v_cvt_pk_bf16_f32 v5, v10, v11
	v_cvt_pk_bf16_f32 v0, v0, v1
	v_cvt_pk_bf16_f32 v1, v2, v3
	ds_write_b64 v139, v[4:5] offset:59168
	ds_write_b64 v139, v[0:1] offset:59232
